# P5 u-pass: coalesced A-operand loads (MFMA rows = expert x 16B-piece; 64B per lane quad), DPP reduce
# speedup vs baseline: 1.0259x; 1.0259x over previous
; __device__ __forceinline__ void peer_token(const Params& P, int t, int lane, int* sidx, float* sval, const int* sid, const float* sgate, const unsigned* szero) {
;     ...
;     {
;         typedef int v8i __attribute__((ext_vector_type(8)));
;         const unsigned char* Ub = P.ws + WS_U;
;         const unsigned lofs = 64u * (unsigned)(lr >> 3) + 16u * (unsigned)g;
;         const unsigned char* bsrc = (lr < 4) ? (((lr & 2) ? slo : shi) + 128 * (lr & 1) + 16 * g) : (const unsigned char*)szero;
;         const int bstep = (lr < 4) ? 256 : 0, bhalf = (lr < 4) ? 64 : 16;
;         v8i Bv[4];
; #pragma unroll
;         for (int st = 0; st < 4; ++st) {
;             const uint4 b0 = *(const uint4*)(bsrc + bstep * st), b1 = *(const uint4*)(bsrc + bstep * st + bhalf);
;             Bv[st] = (v8i){(int)b0.x, (int)b0.y, (int)b0.z, (int)b0.w, (int)b1.x, (int)b1.y, (int)b1.z, (int)b1.w};
;         }
;         __builtin_amdgcn_s_waitcnt(0xc07f);
;         __builtin_amdgcn_wave_barrier();
;         float* sact = (float*)sidx + 128 * (lr & 3) + 4 * (g & 1);
;         const bool owner = (lr < 4) && ((g >> 1) == (lr & 1));
; __global__ void __launch_bounds__(256, 2) mega(Params P) {
;     ...
;     {
;         unsigned* szero = (unsigned*)(smem + 40960);
;         if (tid < 16) szero[tid] = 0u;
;         __syncthreads();
;         unsigned char* res = smem + wave * 10240; unsigned char* work = res + 8192;
;         int* sidx = (int*)work; float* sval = (float*)(work + 1024);
;         int lane5 = lane;
;         asm volatile("" : "+v"(lane5));
;         const int tstride = G * 4;
;         for (int tb = bid * 4 + wave; tb < T2; tb += tstride * 8) {
.LBB0_1375:
	s_or_b64 exec, exec, s[18:19]
	v_cmp_gt_u32_e32 vcc, 16, v0
	s_barrier
	s_and_saveexec_b64 s[0:1], vcc
	v_lshl_add_u32 v0, v0, 2, 0
	v_mov_b32_e32 v2, 0
	ds_write_b32 v0, v2 offset:40960
	s_or_b64 exec, exec, s[0:1]
	s_movk_i32 s20, 0x4000
	v_cmp_gt_i32_e32 vcc, s20, v130
	s_waitcnt lgkmcnt(0)
	s_barrier
	s_and_saveexec_b64 s[0:1], vcc
	s_cbranch_execz .LBB0_1426
	s_movk_i32 s0, 0x2800
	v_and_b32_e32 v115, 7, v131
	v_mad_u32_u24 v114, v1, s0, 0
	v_lshlrev_b32_e32 v0, 7, v115
	v_mov_b32_e32 v1, 0
	v_ashrrev_i32_e32 v2, 3, v131
	v_lshl_add_u64 v[0:1], s[28:29], 0, v[0:1]
	s_mov_b64 s[0:1], 0xc075800
	v_lshl_add_u64 v[100:101], v[0:1], 0, s[0:1]
	v_lshlrev_b32_e32 v0, 10, v2
	v_lshlrev_b32_e32 v1, 6, v115
	s_add_u32 s4, s28, 0x93b3000
	v_add3_u32 v118, v114, v0, v1
	s_addc_u32 s5, s29, 0
	v_lshlrev_b32_e32 v1, 3, v131
	v_and_b32_e32 v3, 2, v131
	v_mul_lo_u32 v116, v2, s22
	s_add_u32 s6, s28, 0xf5a5800
	v_and_b32_e32 v1, 64, v1
	v_and_b32_e32 v2, -16, v131
	v_mov_b32_e32 v4, 0x2000
	v_mov_b32_e32 v5, 0x2400
	v_cmp_eq_u32_e32 vcc, 0, v3
	s_addc_u32 s7, s29, 0
	v_add_u32_e32 v120, v1, v2
	v_lshlrev_b32_e32 v1, 7, v131
	v_cndmask_b32_e32 v3, v4, v5, vcc
	s_add_u32 s8, s28, 0xf595800
	v_add_u32_e32 v3, v114, v3
	v_and_b32_e32 v1, 0x80, v1
	s_addc_u32 s9, s29, 0
	v_and_b32_e32 v0, 15, v131
	v_add3_u32 v2, v3, v1, v2
	v_ashrrev_i32_e32 v3, 5, v131
	v_and_b32_e32 v1, 1, v131
	s_add_u32 s10, s28, 0xe595800
	v_cmp_eq_u32_e32 vcc, v3, v1
	v_cmp_gt_u32_e64 s[2:3], 4, v0
	v_and_b32_e32 v0, 31, v131
	v_lshlrev_b32_e32 v1, 4, v3
	s_addc_u32 s11, s29, 0
	s_and_b64 s[12:13], s[2:3], vcc
	v_lshl_add_u32 v104, v0, 5, v1
	s_add_u32 s14, s28, 0xed95800
	v_ashrrev_i32_e32 v105, 31, v104
	s_addc_u32 s15, s29, 0
	v_lshlrev_b32_e32 v122, 4, v0
	v_lshlrev_b64 v[0:1], 2, v[104:105]
	s_add_i32 s16, 0, 0xa000
	v_lshl_add_u64 v[106:107], s[26:27], 0, v[0:1]
	v_lshl_add_u64 v[108:109], s[44:45], 0, v[0:1]
	v_mov_b32_e32 v0, 0x100
	v_mov_b32_e32 v1, s16
	v_cndmask_b32_e64 v0, 0, v0, s[2:3]
	v_cndmask_b32_e64 v123, v1, v2, s[2:3]
	v_lshlrev_b32_e32 v102, 4, v131
	v_add_u32_e32 v124, v123, v0
	v_lshl_add_u32 v125, v0, 1, v123
	v_mad_u32_u24 v126, v0, 3, v123
	v_lshlrev_b32_e32 v0, 9, v131
	v_add_u32_e32 v119, v114, v102
	v_and_b32_e32 v4, 16, v131
	v_mul_lo_u32 v5, v131, -12
	v_and_b32_e32 v0, 0x600, v0
	v_lshl_add_u32 v117, v131, 5, v114
	v_ashrrev_i32_e32 v103, 31, v102
	v_cndmask_b32_e64 v121, 16, 64, s[2:3]
	v_cmp_gt_u32_e64 s[0:1], 32, v131
	s_lshl_b32 s21, s33, 5
	v_add3_u32 v127, v114, v4, v0
	v_lshlrev_b32_e32 v128, 2, v3
	s_mov_b64 s[2:3], 0
	v_bfrev_b32_e32 v129, 1
	s_movk_i32 s23, 0xff80
	s_movk_i32 s24, 0x7f
	s_movk_i32 s25, 0xff00
	v_mov_b32_e32 v132, 0xffffff00
	s_movk_i32 s26, 0xff
	s_movk_i32 s27, 0xfe
	s_movk_i32 s28, 0xfd
	s_movk_i32 s29, 0xfc
	s_movk_i32 s30, 0xfb
	s_movk_i32 s31, 0xfa
	s_movk_i32 s33, 0xf9
	s_movk_i32 s34, 0xf8
	s_movk_i32 s35, 0xf7
	s_movk_i32 s38, 0xf6
	s_movk_i32 s39, 0xf5
	s_movk_i32 s40, 0xf4
	s_movk_i32 s41, 0xf3
	s_movk_i32 s42, 0xf2
	s_movk_i32 s43, 0xf1
	s_movk_i32 s44, 0xf0
	s_movk_i32 s45, 0xef
	s_movk_i32 s46, 0xee
	s_movk_i32 s47, 0xed
	s_movk_i32 s48, 0xec
	s_movk_i32 s49, 0xeb
	s_movk_i32 s50, 0xea
	s_movk_i32 s51, 0xe9
	s_movk_i32 s52, 0xe8
	s_movk_i32 s53, 0xdf
	s_movk_i32 s54, 0xde
	s_movk_i32 s55, 0xdd
	s_movk_i32 s56, 0xdc
	s_movk_i32 s57, 0xdb
	s_movk_i32 s58, 0xcf
	s_movk_i32 s59, 0xce
	s_movk_i32 s60, 0xcd
	s_movk_i32 s61, 0xcc
	s_movk_i32 s62, 0xbf
	s_movk_i32 s63, 0xbe
	s_movk_i32 s64, 0xbd
	s_movk_i32 s65, 0xaf
	s_movk_i32 s66, 0xae
	s_movk_i32 s67, 0x9f
	s_movk_i32 s68, 0x9e
	s_movk_i32 s69, 0x8f
	s_movk_i32 s70, 0x8e
	s_movk_i32 s71, 0x6f
	s_movk_i32 s72, 0x5f
	s_movk_i32 s73, 0x4f
	v_mov_b32_e32 v133, 0x7f7f7f7f
	s_mov_b32 s74, 0x378e98ab
	s_mov_b32 s75, 0x3b7cd369
	s_mov_b32 s76, 0xbcc618b2
	s_mov_b32 s77, 0x3dda74e4
	s_mov_b32 s78, 0x3f228afd
	s_mov_b32 s79, 0x3e03c728
	s_mov_b32 s80, 0xbfb8aa3b
	s_mov_b32 s81, 0x42ce8ed0
	s_mov_b32 s82, 0xc2b17218
	v_mov_b32_e32 v134, 0x3ba10414
	s_brev_b32 s83, -2
	s_movk_i32 s84, 0x3fff
	v_add_u32_e32 v135, v119, v5
	v_mov_b32_e32 v136, 0xb9c68948
	v_mov_b32_e32 v137, 0x7f800000
	v_lshrrev_b32_e32 v142, 4, v131
	v_and_b32_e32 v143, 3, v131
	v_lshlrev_b32_e32 v144, 6, v142
	v_lshl_add_u32 v144, v143, 4, v144
	v_and_b32_e32 v145, 12, v131
	v_and_b32_e32 v146, 15, v131
	v_lshrrev_b32_e32 v147, 1, v142
	v_lshlrev_b32_e32 v147, 7, v147
	v_and_b32_e32 v148, 1, v142
	v_lshl_add_u32 v147, v148, 4, v147
	v_lshl_add_u32 v147, v143, 5, v147
	v_and_b32_e32 v148, 4, v146
	v_cmp_eq_u32_e32 vcc, 0, v148
	v_mov_b32_e32 v149, 0x400
	s_nop 1
	v_cndmask_b32_e32 v148, 0, v149, vcc
	v_add3_u32 v147, v147, v148, v114
	v_add_u32_e32 v147, 0x2000, v147
	v_cmp_gt_u32_e32 vcc, 8, v146
	v_mov_b32_e32 v149, 0xa000
	v_add_u32_e32 v148, 16, v149
	v_add_u32_e32 v151, 0x100, v147
	v_add_u32_e32 v152, 0x200, v147
	v_add_u32_e32 v153, 0x300, v147
	v_cndmask_b32_e32 v150, v149, v147, vcc
	v_cndmask_b32_e32 v151, v148, v151, vcc
	v_cndmask_b32_e32 v152, v149, v152, vcc
	v_cndmask_b32_e32 v153, v148, v153, vcc
	v_add_u32_e32 v154, 0x2000, v114
	v_lshl_add_u32 v155, v142, 2, v154
	v_lshl_add_u32 v156, v131, 2, v154
	v_add_u32_e32 v156, 0x400, v156
	v_cmp_eq_u32_e32 vcc, 0, v146
	v_and_b32_e32 v157, 11, v146
	s_nop 1
	v_cndmask_b32_e32 v155, v156, v155, vcc
	v_cmp_eq_u32_e32 vcc, 0, v157
	s_nop 1
	v_cndmask_b32_e64 v158, 0, 1.0, vcc
	v_cmp_eq_u32_e32 vcc, 1, v157
	s_nop 1
	v_cndmask_b32_e64 v159, 0, 1.0, vcc
	v_cmp_eq_u32_e32 vcc, 2, v157
	s_nop 1
	v_cndmask_b32_e64 v160, 0, 1.0, vcc
	v_cmp_eq_u32_e32 vcc, 3, v157
	s_nop 1
	v_cndmask_b32_e64 v161, 0, 1.0, vcc
	s_branch .LBB0_1380

; __device__ __forceinline__ void peer_token(const Params& P, int t, int lane, int* sidx, float* sval, const int* sid, const float* sgate, const unsigned* szero) {
;     ...
;     {
;         const uint4 xa = xa_pre, xb = xb_pre;
;         const unsigned xw[8] = {xa.x, xa.y, xa.z, xa.w, xb.x, xb.y, xb.z, xb.w};
;         unsigned hi[4], lo[4];
; #pragma unroll
;         for (int i = 0; i < 4; ++i) {
;             const float x0 = bflo(xw[2 * i]), x1 = bfhi(xw[2 * i]), x2 = bflo(xw[2 * i + 1]), x3 = bfhi(xw[2 * i + 1]);
;             int wd = 0;
;             wd = __builtin_amdgcn_cvt_pk_fp8_f32(x0, x1, wd, false);
;             wd = __builtin_amdgcn_cvt_pk_fp8_f32(x2, x3, wd, true);
;             const f32x2 h01 = __builtin_amdgcn_cvt_pk_f32_fp8(wd, false), h23 = __builtin_amdgcn_cvt_pk_f32_fp8(wd, true);
;             int wl = 0;
;             wl = __builtin_amdgcn_cvt_pk_fp8_f32(x0 - h01.x, x1 - h01.y, wl, false);
;             wl = __builtin_amdgcn_cvt_pk_fp8_f32(x2 - h23.x, x3 - h23.y, wl, true);
;             hi[i] = (unsigned)wd; lo[i] = (unsigned)wl;
;         }
;         *(uint4*)(shi + lane * 16) = make_uint4(hi[0], hi[1], hi[2], hi[3]);
;         *(uint4*)(slo + lane * 16) = make_uint4(lo[0], lo[1], lo[2], lo[3]);
;     }
;     __builtin_amdgcn_s_waitcnt(0xc07f);
;     __builtin_amdgcn_wave_barrier();
;     {
;         typedef int v8i __attribute__((ext_vector_type(8)));
;         const unsigned char* Ub = P.ws + WS_U;
;         const unsigned lofs = 64u * (unsigned)(lr >> 3) + 16u * (unsigned)g;
;         const unsigned char* bsrc = (lr < 4) ? (((lr & 2) ? slo : shi) + 128 * (lr & 1) + 16 * g) : (const unsigned char*)szero;
;         const int bstep = (lr < 4) ? 256 : 0, bhalf = (lr < 4) ? 64 : 16;
;         v8i Bv[4];
; #pragma unroll
;         for (int st = 0; st < 4; ++st) {
;             const uint4 b0 = *(const uint4*)(bsrc + bstep * st), b1 = *(const uint4*)(bsrc + bstep * st + bhalf);
;             Bv[st] = (v8i){(int)b0.x, (int)b0.y, (int)b0.z, (int)b0.w, (int)b1.x, (int)b1.y, (int)b1.z, (int)b1.w};
;         }
;         __builtin_amdgcn_s_waitcnt(0xc07f);
;         __builtin_amdgcn_wave_barrier();
;         float* sact = (float*)sidx + 128 * (lr & 3) + 4 * (g & 1);
;         const bool owner = (lr < 4) && ((g >> 1) == (lr & 1));
;         uint4 abuf[2][2][4];
;         unsigned off2[2];
; #pragma unroll
.LBB0_1382:
	s_mul_i32 s16, s85, s22
	v_add_u32_e32 v112, s16, v130
	v_cmp_gt_i32_e32 vcc, s20, v112
	s_and_saveexec_b64 s[16:17], vcc
	s_cbranch_execz .LBB0_1381
	v_ashrrev_i32_e32 v113, 31, v112
	v_lshlrev_b64 v[0:1], 11, v[112:113]
	v_lshl_add_u64 v[110:111], s[36:37], 0, v[0:1]
	v_lshl_add_u64 v[4:5], v[102:103], 1, v[110:111]
	global_load_dwordx4 v[0:3], v[4:5], off
	s_nop 0
	global_load_dwordx4 v[4:7], v[4:5], off offset:16
	v_mov_b32_e32 v8, 0
	v_mov_b32_e32 v9, 0
	v_mov_b32_e32 v10, 0
	v_mov_b32_e32 v11, 0
	v_mov_b32_e32 v12, 0
	v_mov_b32_e32 v13, 0
	v_mov_b32_e32 v14, 0
	v_mov_b32_e32 v15, 0
	v_lshl_add_u32 v139, s85, 10, v114
	v_add_u32_e32 v26, v123, v121
	v_add_u32_e32 v27, v124, v121
	v_add_u32_e32 v28, v125, v121
	v_add_u32_e32 v32, v126, v121
	v_lshl_add_u64 v[16:17], v[112:113], 2, s[4:5]
	v_lshl_add_u32 v141, v115, 2, v139
	global_load_dword v140, v[16:17], off
	s_waitcnt vmcnt(2)
	v_lshlrev_b32_e32 v29, 16, v0
	v_and_b32_e32 v30, 0xffff0000, v0
	v_lshlrev_b32_e32 v34, 16, v2
	v_and_b32_e32 v35, 0xffff0000, v2
	s_waitcnt vmcnt(1)
	v_lshlrev_b32_e32 v38, 16, v4
	v_and_b32_e32 v39, 0xffff0000, v4
	v_lshlrev_b32_e32 v42, 16, v6
	v_and_b32_e32 v43, 0xffff0000, v6
	v_cvt_pk_fp8_f32 v8, v29, v30
	v_cvt_pk_fp8_f32 v9, v34, v35
	v_cvt_pk_fp8_f32 v10, v38, v39
	v_cvt_pk_fp8_f32 v11, v42, v43
	v_lshlrev_b32_e32 v31, 16, v1
	v_and_b32_e32 v33, 0xffff0000, v1
	v_lshlrev_b32_e32 v36, 16, v3
	v_and_b32_e32 v37, 0xffff0000, v3
	v_lshlrev_b32_e32 v40, 16, v5
	v_and_b32_e32 v41, 0xffff0000, v5
	v_lshlrev_b32_e32 v44, 16, v7
	v_and_b32_e32 v45, 0xffff0000, v7
	v_cvt_pk_fp8_f32 v8, v31, v33 op_sel:[0,0,1]
	v_cvt_pk_fp8_f32 v9, v36, v37 op_sel:[0,0,1]
	v_cvt_pk_fp8_f32 v10, v40, v41 op_sel:[0,0,1]
	v_cvt_pk_fp8_f32 v11, v44, v45 op_sel:[0,0,1]
	v_cvt_pk_f32_fp8_e32 v[0:1], v8
	v_cvt_pk_f32_fp8_e32 v[4:5], v9
	v_cvt_pk_f32_fp8_e32 v[18:19], v10
	v_cvt_pk_f32_fp8_e32 v[22:23], v11
	v_cvt_pk_f32_fp8_sdwa v[2:3], v8 src0_sel:WORD_1
	v_cvt_pk_f32_fp8_sdwa v[6:7], v9 src0_sel:WORD_1
	v_cvt_pk_f32_fp8_sdwa v[20:21], v10 src0_sel:WORD_1
	v_cvt_pk_f32_fp8_sdwa v[24:25], v11 src0_sel:WORD_1
	v_sub_f32_e32 v0, v29, v0
	v_sub_f32_e32 v1, v30, v1
	v_sub_f32_e32 v4, v34, v4
	v_sub_f32_e32 v5, v35, v5
	v_sub_f32_e32 v18, v38, v18
	v_sub_f32_e32 v19, v39, v19
	v_sub_f32_e32 v22, v42, v22
	v_sub_f32_e32 v23, v43, v23
	v_cvt_pk_fp8_f32 v12, v0, v1
	v_cvt_pk_fp8_f32 v13, v4, v5
	v_cvt_pk_fp8_f32 v14, v18, v19
	v_cvt_pk_fp8_f32 v15, v22, v23
	v_sub_f32_e32 v2, v31, v2
	v_sub_f32_e32 v3, v33, v3
	v_sub_f32_e32 v6, v36, v6
	v_sub_f32_e32 v7, v37, v7
	v_sub_f32_e32 v20, v40, v20
	v_sub_f32_e32 v21, v41, v21
	v_sub_f32_e32 v24, v44, v24
	v_sub_f32_e32 v25, v45, v25
	v_cvt_pk_fp8_f32 v12, v2, v3 op_sel:[0,0,1]
	v_cvt_pk_fp8_f32 v13, v6, v7 op_sel:[0,0,1]
	v_cvt_pk_fp8_f32 v14, v20, v21 op_sel:[0,0,1]
	v_cvt_pk_fp8_f32 v15, v24, v25 op_sel:[0,0,1]
	ds_write_b128 v119, v[8:11] offset:9216
	ds_write_b128 v119, v[12:15] offset:8192
	s_waitcnt lgkmcnt(0)
	ds_read_b128 v[162:165], v150
	ds_read_b128 v[166:169], v151
	ds_read_b128 v[170:173], v152
	ds_read_b128 v[174:177], v153
	v_add_u32_e32 v178, v139, v145
	s_waitcnt lgkmcnt(0)
	ds_read2_b32 v[180:181], v178 offset1:4
	ds_read2_b32 v[182:183], v178 offset0:8 offset1:12
	s_waitcnt lgkmcnt(0)
	v_lshl_add_u32 v180, v180, 9, v144
	v_lshl_add_u32 v181, v181, 9, v144
	v_lshl_add_u32 v182, v182, 9, v144
	v_lshl_add_u32 v183, v183, 9, v144
	global_load_dwordx4 v[0:3], v180, s[10:11]
	global_load_dwordx4 v[4:7], v180, s[10:11] offset:256
	global_load_dwordx4 v[8:11], v181, s[10:11]
	global_load_dwordx4 v[12:15], v181, s[10:11] offset:256
	global_load_dwordx4 v[16:19], v182, s[10:11]
	global_load_dwordx4 v[20:23], v182, s[10:11] offset:256
	global_load_dwordx4 v[24:27], v183, s[10:11]
	global_load_dwordx4 v[28:31], v183, s[10:11] offset:256
	ds_read2_b32 v[184:185], v178 offset0:16 offset1:20
	ds_read2_b32 v[186:187], v178 offset0:24 offset1:28
	s_waitcnt lgkmcnt(0)
	v_lshl_add_u32 v184, v184, 9, v144
	v_lshl_add_u32 v185, v185, 9, v144
	v_lshl_add_u32 v186, v186, 9, v144
	v_lshl_add_u32 v187, v187, 9, v144
	global_load_dwordx4 v[32:35], v184, s[10:11]
	global_load_dwordx4 v[36:39], v184, s[10:11] offset:256
	global_load_dwordx4 v[40:43], v185, s[10:11]
	global_load_dwordx4 v[44:47], v185, s[10:11] offset:256
	global_load_dwordx4 v[48:51], v186, s[10:11]
	global_load_dwordx4 v[52:55], v186, s[10:11] offset:256
	global_load_dwordx4 v[56:59], v187, s[10:11]
	global_load_dwordx4 v[60:63], v187, s[10:11] offset:256
	s_waitcnt vmcnt(8)
	v_mfma_scale_f32_16x16x128_f8f6f4 v[64:67], v[0:3], v[162:169], 0, v133, v133 op_sel_hi:[0,0,0] cbsz:4
	v_mfma_scale_f32_16x16x128_f8f6f4 v[64:67], v[4:7], v[170:177], v[64:67], v133, v133 op_sel_hi:[0,0,0] cbsz:4
	v_mfma_scale_f32_16x16x128_f8f6f4 v[68:71], v[8:11], v[162:169], 0, v133, v133 op_sel_hi:[0,0,0] cbsz:4
	v_mfma_scale_f32_16x16x128_f8f6f4 v[68:71], v[12:15], v[170:177], v[68:71], v133, v133 op_sel_hi:[0,0,0] cbsz:4
	v_mfma_scale_f32_16x16x128_f8f6f4 v[72:75], v[16:19], v[162:169], 0, v133, v133 op_sel_hi:[0,0,0] cbsz:4
	v_mfma_scale_f32_16x16x128_f8f6f4 v[72:75], v[20:23], v[170:177], v[72:75], v133, v133 op_sel_hi:[0,0,0] cbsz:4
	v_mfma_scale_f32_16x16x128_f8f6f4 v[76:79], v[24:27], v[162:169], 0, v133, v133 op_sel_hi:[0,0,0] cbsz:4
	v_mfma_scale_f32_16x16x128_f8f6f4 v[76:79], v[28:31], v[170:177], v[76:79], v133, v133 op_sel_hi:[0,0,0] cbsz:4
	ds_read2_b32 v[180:181], v178 offset0:32 offset1:36
	ds_read2_b32 v[182:183], v178 offset0:40 offset1:44
	s_waitcnt lgkmcnt(0)
; __device__ __forceinline__ void peer_token(const Params& P, int t, int lane, int* sidx, float* sval, const int* sid, const float* sgate, const unsigned* szero) {
;     ...
;         for (int hh = 0; hh < 2; ++hh)
; #pragma unroll
;             for (int st = 0; st < 4; ++st) abuf[0][hh][st] = *(const uint4*)(Ub + (off2[hh] + 128 * st));
; #pragma unroll
;         for (int T = 0; T < 8; ++T) {
;             if (T + 1 < 8) {
; #pragma unroll
;                 for (int hh = 0; hh < 2; ++hh) off2[hh] = (unsigned)sid[16 * (T + 1) + 8 * hh + (lr & 7)] * 512u + lofs;
; #pragma unroll
;                 for (int hh = 0; hh < 2; ++hh)
; #pragma unroll
;                     for (int st = 0; st < 4; ++st) abuf[(T + 1) & 1][hh][st] = *(const uint4*)(Ub + (off2[hh] + 128 * st));
;             }
; #pragma unroll
;             for (int hh = 0; hh < 2; ++hh) {
;                 f32x4 au = (f32x4){0.f, 0.f, 0.f, 0.f};
; #pragma unroll
;                 for (int st = 0; st < 4; ++st) {
;                     const uint4 a4 = abuf[T & 1][hh][st];
;                     const v8i Av = {(int)a4.x, (int)a4.y, (int)a4.z, (int)a4.w, 0, 0, 0, 0};
;                     au = __builtin_amdgcn_mfma_scale_f32_16x16x128_f8f6f4(Av, Bv[st], au, 4, 0, 0, 0x7f7f7f7f, 0, 0x7f7f7f7f);
;                 }
;                 if (owner) *(f32x4*)(sact + 16 * T + 8 * hh) = au;
;             }
;         }
	v_lshl_add_u32 v180, v180, 9, v144
	v_lshl_add_u32 v181, v181, 9, v144
	v_lshl_add_u32 v182, v182, 9, v144
	v_lshl_add_u32 v183, v183, 9, v144
	global_load_dwordx4 v[0:3], v180, s[10:11]
	global_load_dwordx4 v[4:7], v180, s[10:11] offset:256
	global_load_dwordx4 v[8:11], v181, s[10:11]
	global_load_dwordx4 v[12:15], v181, s[10:11] offset:256
	global_load_dwordx4 v[16:19], v182, s[10:11]
	global_load_dwordx4 v[20:23], v182, s[10:11] offset:256
	global_load_dwordx4 v[24:27], v183, s[10:11]
	global_load_dwordx4 v[28:31], v183, s[10:11] offset:256
	s_waitcnt vmcnt(8)
	v_mfma_scale_f32_16x16x128_f8f6f4 v[80:83], v[32:35], v[162:169], 0, v133, v133 op_sel_hi:[0,0,0] cbsz:4
	v_mfma_scale_f32_16x16x128_f8f6f4 v[80:83], v[36:39], v[170:177], v[80:83], v133, v133 op_sel_hi:[0,0,0] cbsz:4
	v_mfma_scale_f32_16x16x128_f8f6f4 v[84:87], v[40:43], v[162:169], 0, v133, v133 op_sel_hi:[0,0,0] cbsz:4
	v_mfma_scale_f32_16x16x128_f8f6f4 v[84:87], v[44:47], v[170:177], v[84:87], v133, v133 op_sel_hi:[0,0,0] cbsz:4
	v_mfma_scale_f32_16x16x128_f8f6f4 v[88:91], v[48:51], v[162:169], 0, v133, v133 op_sel_hi:[0,0,0] cbsz:4
	v_mfma_scale_f32_16x16x128_f8f6f4 v[88:91], v[52:55], v[170:177], v[88:91], v133, v133 op_sel_hi:[0,0,0] cbsz:4
	v_mfma_scale_f32_16x16x128_f8f6f4 v[92:95], v[56:59], v[162:169], 0, v133, v133 op_sel_hi:[0,0,0] cbsz:4
	v_mfma_scale_f32_16x16x128_f8f6f4 v[92:95], v[60:63], v[170:177], v[92:95], v133, v133 op_sel_hi:[0,0,0] cbsz:4
	s_nop 3
	v_mul_f32_e32 v188, v158, v64
	v_mul_f32_e32 v189, v158, v68
	v_mul_f32_e32 v190, v158, v72
	v_mul_f32_e32 v191, v158, v76
	v_fmac_f32_e32 v188, v159, v65
	v_fmac_f32_e32 v189, v159, v69
	v_fmac_f32_e32 v190, v159, v73
	v_fmac_f32_e32 v191, v159, v77
	v_fmac_f32_e32 v188, v160, v66
	v_fmac_f32_e32 v189, v160, v70
	v_fmac_f32_e32 v190, v160, v74
	v_fmac_f32_e32 v191, v160, v78
	v_fmac_f32_e32 v188, v161, v67
	v_fmac_f32_e32 v189, v161, v71
	v_fmac_f32_e32 v190, v161, v75
	v_fmac_f32_e32 v191, v161, v79
	v_add_f32_dpp v188, v188, v188 quad_perm:[1,0,3,2] row_mask:0xf bank_mask:0xf
	v_add_f32_dpp v189, v189, v189 quad_perm:[1,0,3,2] row_mask:0xf bank_mask:0xf
	v_add_f32_dpp v190, v190, v190 quad_perm:[1,0,3,2] row_mask:0xf bank_mask:0xf
	v_add_f32_dpp v191, v191, v191 quad_perm:[1,0,3,2] row_mask:0xf bank_mask:0xf
	v_add_f32_dpp v188, v188, v188 quad_perm:[2,3,0,1] row_mask:0xf bank_mask:0xf
	v_add_f32_dpp v189, v189, v189 quad_perm:[2,3,0,1] row_mask:0xf bank_mask:0xf
	v_add_f32_dpp v190, v190, v190 quad_perm:[2,3,0,1] row_mask:0xf bank_mask:0xf
	v_add_f32_dpp v191, v191, v191 quad_perm:[2,3,0,1] row_mask:0xf bank_mask:0xf
	v_add_f32_dpp v188, v188, v188 row_half_mirror row_mask:0xf bank_mask:0xf
	v_add_f32_dpp v189, v189, v189 row_half_mirror row_mask:0xf bank_mask:0xf
	v_add_f32_dpp v190, v190, v190 row_half_mirror row_mask:0xf bank_mask:0xf
	v_add_f32_dpp v191, v191, v191 row_half_mirror row_mask:0xf bank_mask:0xf
	ds_write_b32 v155, v188
	ds_write_b32 v155, v189 offset:16
	ds_write_b32 v155, v190 offset:32
	ds_write_b32 v155, v191 offset:48
	ds_read2_b32 v[184:185], v178 offset0:48 offset1:52
	ds_read2_b32 v[186:187], v178 offset0:56 offset1:60
	s_waitcnt lgkmcnt(0)
	v_lshl_add_u32 v184, v184, 9, v144
	v_lshl_add_u32 v185, v185, 9, v144
	v_lshl_add_u32 v186, v186, 9, v144
	v_lshl_add_u32 v187, v187, 9, v144
	global_load_dwordx4 v[32:35], v184, s[10:11]
	global_load_dwordx4 v[36:39], v184, s[10:11] offset:256
	global_load_dwordx4 v[40:43], v185, s[10:11]
	global_load_dwordx4 v[44:47], v185, s[10:11] offset:256
	global_load_dwordx4 v[48:51], v186, s[10:11]
	global_load_dwordx4 v[52:55], v186, s[10:11] offset:256
	global_load_dwordx4 v[56:59], v187, s[10:11]
	global_load_dwordx4 v[60:63], v187, s[10:11] offset:256
	s_waitcnt vmcnt(8)
	v_mfma_scale_f32_16x16x128_f8f6f4 v[64:67], v[0:3], v[162:169], 0, v133, v133 op_sel_hi:[0,0,0] cbsz:4
	v_mfma_scale_f32_16x16x128_f8f6f4 v[64:67], v[4:7], v[170:177], v[64:67], v133, v133 op_sel_hi:[0,0,0] cbsz:4
	v_mfma_scale_f32_16x16x128_f8f6f4 v[68:71], v[8:11], v[162:169], 0, v133, v133 op_sel_hi:[0,0,0] cbsz:4
	v_mfma_scale_f32_16x16x128_f8f6f4 v[68:71], v[12:15], v[170:177], v[68:71], v133, v133 op_sel_hi:[0,0,0] cbsz:4
	v_mfma_scale_f32_16x16x128_f8f6f4 v[72:75], v[16:19], v[162:169], 0, v133, v133 op_sel_hi:[0,0,0] cbsz:4
	v_mfma_scale_f32_16x16x128_f8f6f4 v[72:75], v[20:23], v[170:177], v[72:75], v133, v133 op_sel_hi:[0,0,0] cbsz:4
	v_mfma_scale_f32_16x16x128_f8f6f4 v[76:79], v[24:27], v[162:169], 0, v133, v133 op_sel_hi:[0,0,0] cbsz:4
	v_mfma_scale_f32_16x16x128_f8f6f4 v[76:79], v[28:31], v[170:177], v[76:79], v133, v133 op_sel_hi:[0,0,0] cbsz:4
	s_nop 3
	v_mul_f32_e32 v188, v158, v80
	v_mul_f32_e32 v189, v158, v84
	v_mul_f32_e32 v190, v158, v88
	v_mul_f32_e32 v191, v158, v92
	v_fmac_f32_e32 v188, v159, v81
	v_fmac_f32_e32 v189, v159, v85
	v_fmac_f32_e32 v190, v159, v89
	v_fmac_f32_e32 v191, v159, v93
	v_fmac_f32_e32 v188, v160, v82
	v_fmac_f32_e32 v189, v160, v86
	v_fmac_f32_e32 v190, v160, v90
	v_fmac_f32_e32 v191, v160, v94
	v_fmac_f32_e32 v188, v161, v83
	v_fmac_f32_e32 v189, v161, v87
	v_fmac_f32_e32 v190, v161, v91
	v_fmac_f32_e32 v191, v161, v95
	v_add_f32_dpp v188, v188, v188 quad_perm:[1,0,3,2] row_mask:0xf bank_mask:0xf
	v_add_f32_dpp v189, v189, v189 quad_perm:[1,0,3,2] row_mask:0xf bank_mask:0xf
	v_add_f32_dpp v190, v190, v190 quad_perm:[1,0,3,2] row_mask:0xf bank_mask:0xf
	v_add_f32_dpp v191, v191, v191 quad_perm:[1,0,3,2] row_mask:0xf bank_mask:0xf
	v_add_f32_dpp v188, v188, v188 quad_perm:[2,3,0,1] row_mask:0xf bank_mask:0xf
	v_add_f32_dpp v189, v189, v189 quad_perm:[2,3,0,1] row_mask:0xf bank_mask:0xf
	v_add_f32_dpp v190, v190, v190 quad_perm:[2,3,0,1] row_mask:0xf bank_mask:0xf
	v_add_f32_dpp v191, v191, v191 quad_perm:[2,3,0,1] row_mask:0xf bank_mask:0xf
	v_add_f32_dpp v188, v188, v188 row_half_mirror row_mask:0xf bank_mask:0xf
	v_add_f32_dpp v189, v189, v189 row_half_mirror row_mask:0xf bank_mask:0xf
	v_add_f32_dpp v190, v190, v190 row_half_mirror row_mask:0xf bank_mask:0xf
	v_add_f32_dpp v191, v191, v191 row_half_mirror row_mask:0xf bank_mask:0xf
	ds_write_b32 v155, v188 offset:64
	ds_write_b32 v155, v189 offset:80
	ds_write_b32 v155, v190 offset:96
	ds_write_b32 v155, v191 offset:112
	ds_read2_b32 v[180:181], v178 offset0:64 offset1:68
	ds_read2_b32 v[182:183], v178 offset0:72 offset1:76
	s_waitcnt lgkmcnt(0)
; __device__ __forceinline__ void peer_token(const Params& P, int t, int lane, int* sidx, float* sval, const int* sid, const float* sgate, const unsigned* szero) {
;     ...
;         for (int hh = 0; hh < 2; ++hh)
; #pragma unroll
;             for (int st = 0; st < 4; ++st) abuf[0][hh][st] = *(const uint4*)(Ub + (off2[hh] + 128 * st));
; #pragma unroll
;         for (int T = 0; T < 8; ++T) {
;             if (T + 1 < 8) {
; #pragma unroll
;                 for (int hh = 0; hh < 2; ++hh) off2[hh] = (unsigned)sid[16 * (T + 1) + 8 * hh + (lr & 7)] * 512u + lofs;
; #pragma unroll
;                 for (int hh = 0; hh < 2; ++hh)
; #pragma unroll
;                     for (int st = 0; st < 4; ++st) abuf[(T + 1) & 1][hh][st] = *(const uint4*)(Ub + (off2[hh] + 128 * st));
;             }
; #pragma unroll
;             for (int hh = 0; hh < 2; ++hh) {
;                 f32x4 au = (f32x4){0.f, 0.f, 0.f, 0.f};
; #pragma unroll
;                 for (int st = 0; st < 4; ++st) {
;                     const uint4 a4 = abuf[T & 1][hh][st];
;                     const v8i Av = {(int)a4.x, (int)a4.y, (int)a4.z, (int)a4.w, 0, 0, 0, 0};
;                     au = __builtin_amdgcn_mfma_scale_f32_16x16x128_f8f6f4(Av, Bv[st], au, 4, 0, 0, 0x7f7f7f7f, 0, 0x7f7f7f7f);
;                 }
;                 if (owner) *(f32x4*)(sact + 16 * T + 8 * hh) = au;
;             }
;         }
	v_lshl_add_u32 v180, v180, 9, v144
	v_lshl_add_u32 v181, v181, 9, v144
	v_lshl_add_u32 v182, v182, 9, v144
	v_lshl_add_u32 v183, v183, 9, v144
	global_load_dwordx4 v[0:3], v180, s[10:11]
	global_load_dwordx4 v[4:7], v180, s[10:11] offset:256
	global_load_dwordx4 v[8:11], v181, s[10:11]
	global_load_dwordx4 v[12:15], v181, s[10:11] offset:256
	global_load_dwordx4 v[16:19], v182, s[10:11]
	global_load_dwordx4 v[20:23], v182, s[10:11] offset:256
	global_load_dwordx4 v[24:27], v183, s[10:11]
	global_load_dwordx4 v[28:31], v183, s[10:11] offset:256
	s_waitcnt vmcnt(8)
	v_mfma_scale_f32_16x16x128_f8f6f4 v[80:83], v[32:35], v[162:169], 0, v133, v133 op_sel_hi:[0,0,0] cbsz:4
	v_mfma_scale_f32_16x16x128_f8f6f4 v[80:83], v[36:39], v[170:177], v[80:83], v133, v133 op_sel_hi:[0,0,0] cbsz:4
	v_mfma_scale_f32_16x16x128_f8f6f4 v[84:87], v[40:43], v[162:169], 0, v133, v133 op_sel_hi:[0,0,0] cbsz:4
	v_mfma_scale_f32_16x16x128_f8f6f4 v[84:87], v[44:47], v[170:177], v[84:87], v133, v133 op_sel_hi:[0,0,0] cbsz:4
	v_mfma_scale_f32_16x16x128_f8f6f4 v[88:91], v[48:51], v[162:169], 0, v133, v133 op_sel_hi:[0,0,0] cbsz:4
	v_mfma_scale_f32_16x16x128_f8f6f4 v[88:91], v[52:55], v[170:177], v[88:91], v133, v133 op_sel_hi:[0,0,0] cbsz:4
	v_mfma_scale_f32_16x16x128_f8f6f4 v[92:95], v[56:59], v[162:169], 0, v133, v133 op_sel_hi:[0,0,0] cbsz:4
	v_mfma_scale_f32_16x16x128_f8f6f4 v[92:95], v[60:63], v[170:177], v[92:95], v133, v133 op_sel_hi:[0,0,0] cbsz:4
	s_nop 3
	v_mul_f32_e32 v188, v158, v64
	v_mul_f32_e32 v189, v158, v68
	v_mul_f32_e32 v190, v158, v72
	v_mul_f32_e32 v191, v158, v76
	v_fmac_f32_e32 v188, v159, v65
	v_fmac_f32_e32 v189, v159, v69
	v_fmac_f32_e32 v190, v159, v73
	v_fmac_f32_e32 v191, v159, v77
	v_fmac_f32_e32 v188, v160, v66
	v_fmac_f32_e32 v189, v160, v70
	v_fmac_f32_e32 v190, v160, v74
	v_fmac_f32_e32 v191, v160, v78
	v_fmac_f32_e32 v188, v161, v67
	v_fmac_f32_e32 v189, v161, v71
	v_fmac_f32_e32 v190, v161, v75
	v_fmac_f32_e32 v191, v161, v79
	v_add_f32_dpp v188, v188, v188 quad_perm:[1,0,3,2] row_mask:0xf bank_mask:0xf
	v_add_f32_dpp v189, v189, v189 quad_perm:[1,0,3,2] row_mask:0xf bank_mask:0xf
	v_add_f32_dpp v190, v190, v190 quad_perm:[1,0,3,2] row_mask:0xf bank_mask:0xf
	v_add_f32_dpp v191, v191, v191 quad_perm:[1,0,3,2] row_mask:0xf bank_mask:0xf
	v_add_f32_dpp v188, v188, v188 quad_perm:[2,3,0,1] row_mask:0xf bank_mask:0xf
	v_add_f32_dpp v189, v189, v189 quad_perm:[2,3,0,1] row_mask:0xf bank_mask:0xf
	v_add_f32_dpp v190, v190, v190 quad_perm:[2,3,0,1] row_mask:0xf bank_mask:0xf
	v_add_f32_dpp v191, v191, v191 quad_perm:[2,3,0,1] row_mask:0xf bank_mask:0xf
	v_add_f32_dpp v188, v188, v188 row_half_mirror row_mask:0xf bank_mask:0xf
	v_add_f32_dpp v189, v189, v189 row_half_mirror row_mask:0xf bank_mask:0xf
	v_add_f32_dpp v190, v190, v190 row_half_mirror row_mask:0xf bank_mask:0xf
	v_add_f32_dpp v191, v191, v191 row_half_mirror row_mask:0xf bank_mask:0xf
	ds_write_b32 v155, v188 offset:128
	ds_write_b32 v155, v189 offset:144
	ds_write_b32 v155, v190 offset:160
	ds_write_b32 v155, v191 offset:176
	ds_read2_b32 v[184:185], v178 offset0:80 offset1:84
	ds_read2_b32 v[186:187], v178 offset0:88 offset1:92
	s_waitcnt lgkmcnt(0)
	v_lshl_add_u32 v184, v184, 9, v144
	v_lshl_add_u32 v185, v185, 9, v144
	v_lshl_add_u32 v186, v186, 9, v144
	v_lshl_add_u32 v187, v187, 9, v144
	global_load_dwordx4 v[32:35], v184, s[10:11]
	global_load_dwordx4 v[36:39], v184, s[10:11] offset:256
	global_load_dwordx4 v[40:43], v185, s[10:11]
	global_load_dwordx4 v[44:47], v185, s[10:11] offset:256
	global_load_dwordx4 v[48:51], v186, s[10:11]
	global_load_dwordx4 v[52:55], v186, s[10:11] offset:256
	global_load_dwordx4 v[56:59], v187, s[10:11]
	global_load_dwordx4 v[60:63], v187, s[10:11] offset:256
	s_waitcnt vmcnt(8)
	v_mfma_scale_f32_16x16x128_f8f6f4 v[64:67], v[0:3], v[162:169], 0, v133, v133 op_sel_hi:[0,0,0] cbsz:4
	v_mfma_scale_f32_16x16x128_f8f6f4 v[64:67], v[4:7], v[170:177], v[64:67], v133, v133 op_sel_hi:[0,0,0] cbsz:4
	v_mfma_scale_f32_16x16x128_f8f6f4 v[68:71], v[8:11], v[162:169], 0, v133, v133 op_sel_hi:[0,0,0] cbsz:4
	v_mfma_scale_f32_16x16x128_f8f6f4 v[68:71], v[12:15], v[170:177], v[68:71], v133, v133 op_sel_hi:[0,0,0] cbsz:4
	v_mfma_scale_f32_16x16x128_f8f6f4 v[72:75], v[16:19], v[162:169], 0, v133, v133 op_sel_hi:[0,0,0] cbsz:4
	v_mfma_scale_f32_16x16x128_f8f6f4 v[72:75], v[20:23], v[170:177], v[72:75], v133, v133 op_sel_hi:[0,0,0] cbsz:4
	v_mfma_scale_f32_16x16x128_f8f6f4 v[76:79], v[24:27], v[162:169], 0, v133, v133 op_sel_hi:[0,0,0] cbsz:4
	v_mfma_scale_f32_16x16x128_f8f6f4 v[76:79], v[28:31], v[170:177], v[76:79], v133, v133 op_sel_hi:[0,0,0] cbsz:4
	s_nop 3
	v_mul_f32_e32 v188, v158, v80
	v_mul_f32_e32 v189, v158, v84
	v_mul_f32_e32 v190, v158, v88
	v_mul_f32_e32 v191, v158, v92
	v_fmac_f32_e32 v188, v159, v81
	v_fmac_f32_e32 v189, v159, v85
	v_fmac_f32_e32 v190, v159, v89
	v_fmac_f32_e32 v191, v159, v93
	v_fmac_f32_e32 v188, v160, v82
	v_fmac_f32_e32 v189, v160, v86
	v_fmac_f32_e32 v190, v160, v90
	v_fmac_f32_e32 v191, v160, v94
	v_fmac_f32_e32 v188, v161, v83
	v_fmac_f32_e32 v189, v161, v87
	v_fmac_f32_e32 v190, v161, v91
	v_fmac_f32_e32 v191, v161, v95
	v_add_f32_dpp v188, v188, v188 quad_perm:[1,0,3,2] row_mask:0xf bank_mask:0xf
	v_add_f32_dpp v189, v189, v189 quad_perm:[1,0,3,2] row_mask:0xf bank_mask:0xf
	v_add_f32_dpp v190, v190, v190 quad_perm:[1,0,3,2] row_mask:0xf bank_mask:0xf
	v_add_f32_dpp v191, v191, v191 quad_perm:[1,0,3,2] row_mask:0xf bank_mask:0xf
	v_add_f32_dpp v188, v188, v188 quad_perm:[2,3,0,1] row_mask:0xf bank_mask:0xf
	v_add_f32_dpp v189, v189, v189 quad_perm:[2,3,0,1] row_mask:0xf bank_mask:0xf
	v_add_f32_dpp v190, v190, v190 quad_perm:[2,3,0,1] row_mask:0xf bank_mask:0xf
	v_add_f32_dpp v191, v191, v191 quad_perm:[2,3,0,1] row_mask:0xf bank_mask:0xf
	v_add_f32_dpp v188, v188, v188 row_half_mirror row_mask:0xf bank_mask:0xf
	v_add_f32_dpp v189, v189, v189 row_half_mirror row_mask:0xf bank_mask:0xf
	v_add_f32_dpp v190, v190, v190 row_half_mirror row_mask:0xf bank_mask:0xf
	v_add_f32_dpp v191, v191, v191 row_half_mirror row_mask:0xf bank_mask:0xf
	ds_write_b32 v155, v188 offset:192
	ds_write_b32 v155, v189 offset:208
	ds_write_b32 v155, v190 offset:224
	ds_write_b32 v155, v191 offset:240
	ds_read2_b32 v[180:181], v178 offset0:96 offset1:100
	ds_read2_b32 v[182:183], v178 offset0:104 offset1:108
	s_waitcnt lgkmcnt(0)
; __device__ __forceinline__ void peer_token(const Params& P, int t, int lane, int* sidx, float* sval, const int* sid, const float* sgate, const unsigned* szero) {
;     ...
;         for (int hh = 0; hh < 2; ++hh)
; #pragma unroll
;             for (int st = 0; st < 4; ++st) abuf[0][hh][st] = *(const uint4*)(Ub + (off2[hh] + 128 * st));
; #pragma unroll
;         for (int T = 0; T < 8; ++T) {
;             if (T + 1 < 8) {
; #pragma unroll
;                 for (int hh = 0; hh < 2; ++hh) off2[hh] = (unsigned)sid[16 * (T + 1) + 8 * hh + (lr & 7)] * 512u + lofs;
; #pragma unroll
;                 for (int hh = 0; hh < 2; ++hh)
; #pragma unroll
;                     for (int st = 0; st < 4; ++st) abuf[(T + 1) & 1][hh][st] = *(const uint4*)(Ub + (off2[hh] + 128 * st));
;             }
; #pragma unroll
;             for (int hh = 0; hh < 2; ++hh) {
;                 f32x4 au = (f32x4){0.f, 0.f, 0.f, 0.f};
; #pragma unroll
;                 for (int st = 0; st < 4; ++st) {
;                     const uint4 a4 = abuf[T & 1][hh][st];
;                     const v8i Av = {(int)a4.x, (int)a4.y, (int)a4.z, (int)a4.w, 0, 0, 0, 0};
;                     au = __builtin_amdgcn_mfma_scale_f32_16x16x128_f8f6f4(Av, Bv[st], au, 4, 0, 0, 0x7f7f7f7f, 0, 0x7f7f7f7f);
;                 }
;                 if (owner) *(f32x4*)(sact + 16 * T + 8 * hh) = au;
;             }
;         }
	v_lshl_add_u32 v180, v180, 9, v144
	v_lshl_add_u32 v181, v181, 9, v144
	v_lshl_add_u32 v182, v182, 9, v144
	v_lshl_add_u32 v183, v183, 9, v144
	global_load_dwordx4 v[0:3], v180, s[10:11]
	global_load_dwordx4 v[4:7], v180, s[10:11] offset:256
	global_load_dwordx4 v[8:11], v181, s[10:11]
	global_load_dwordx4 v[12:15], v181, s[10:11] offset:256
	global_load_dwordx4 v[16:19], v182, s[10:11]
	global_load_dwordx4 v[20:23], v182, s[10:11] offset:256
	global_load_dwordx4 v[24:27], v183, s[10:11]
	global_load_dwordx4 v[28:31], v183, s[10:11] offset:256
	s_waitcnt vmcnt(8)
	v_mfma_scale_f32_16x16x128_f8f6f4 v[80:83], v[32:35], v[162:169], 0, v133, v133 op_sel_hi:[0,0,0] cbsz:4
	v_mfma_scale_f32_16x16x128_f8f6f4 v[80:83], v[36:39], v[170:177], v[80:83], v133, v133 op_sel_hi:[0,0,0] cbsz:4
	v_mfma_scale_f32_16x16x128_f8f6f4 v[84:87], v[40:43], v[162:169], 0, v133, v133 op_sel_hi:[0,0,0] cbsz:4
	v_mfma_scale_f32_16x16x128_f8f6f4 v[84:87], v[44:47], v[170:177], v[84:87], v133, v133 op_sel_hi:[0,0,0] cbsz:4
	v_mfma_scale_f32_16x16x128_f8f6f4 v[88:91], v[48:51], v[162:169], 0, v133, v133 op_sel_hi:[0,0,0] cbsz:4
	v_mfma_scale_f32_16x16x128_f8f6f4 v[88:91], v[52:55], v[170:177], v[88:91], v133, v133 op_sel_hi:[0,0,0] cbsz:4
	v_mfma_scale_f32_16x16x128_f8f6f4 v[92:95], v[56:59], v[162:169], 0, v133, v133 op_sel_hi:[0,0,0] cbsz:4
	v_mfma_scale_f32_16x16x128_f8f6f4 v[92:95], v[60:63], v[170:177], v[92:95], v133, v133 op_sel_hi:[0,0,0] cbsz:4
	s_nop 3
	v_mul_f32_e32 v188, v158, v64
	v_mul_f32_e32 v189, v158, v68
	v_mul_f32_e32 v190, v158, v72
	v_mul_f32_e32 v191, v158, v76
	v_fmac_f32_e32 v188, v159, v65
	v_fmac_f32_e32 v189, v159, v69
	v_fmac_f32_e32 v190, v159, v73
	v_fmac_f32_e32 v191, v159, v77
	v_fmac_f32_e32 v188, v160, v66
	v_fmac_f32_e32 v189, v160, v70
	v_fmac_f32_e32 v190, v160, v74
	v_fmac_f32_e32 v191, v160, v78
	v_fmac_f32_e32 v188, v161, v67
	v_fmac_f32_e32 v189, v161, v71
	v_fmac_f32_e32 v190, v161, v75
	v_fmac_f32_e32 v191, v161, v79
	v_add_f32_dpp v188, v188, v188 quad_perm:[1,0,3,2] row_mask:0xf bank_mask:0xf
	v_add_f32_dpp v189, v189, v189 quad_perm:[1,0,3,2] row_mask:0xf bank_mask:0xf
	v_add_f32_dpp v190, v190, v190 quad_perm:[1,0,3,2] row_mask:0xf bank_mask:0xf
	v_add_f32_dpp v191, v191, v191 quad_perm:[1,0,3,2] row_mask:0xf bank_mask:0xf
	v_add_f32_dpp v188, v188, v188 quad_perm:[2,3,0,1] row_mask:0xf bank_mask:0xf
	v_add_f32_dpp v189, v189, v189 quad_perm:[2,3,0,1] row_mask:0xf bank_mask:0xf
	v_add_f32_dpp v190, v190, v190 quad_perm:[2,3,0,1] row_mask:0xf bank_mask:0xf
	v_add_f32_dpp v191, v191, v191 quad_perm:[2,3,0,1] row_mask:0xf bank_mask:0xf
	v_add_f32_dpp v188, v188, v188 row_half_mirror row_mask:0xf bank_mask:0xf
	v_add_f32_dpp v189, v189, v189 row_half_mirror row_mask:0xf bank_mask:0xf
	v_add_f32_dpp v190, v190, v190 row_half_mirror row_mask:0xf bank_mask:0xf
	v_add_f32_dpp v191, v191, v191 row_half_mirror row_mask:0xf bank_mask:0xf
	ds_write_b32 v155, v188 offset:256
	ds_write_b32 v155, v189 offset:272
	ds_write_b32 v155, v190 offset:288
	ds_write_b32 v155, v191 offset:304
	ds_read2_b32 v[184:185], v178 offset0:112 offset1:116
	ds_read2_b32 v[186:187], v178 offset0:120 offset1:124
	s_waitcnt lgkmcnt(0)
	v_lshl_add_u32 v184, v184, 9, v144
	v_lshl_add_u32 v185, v185, 9, v144
	v_lshl_add_u32 v186, v186, 9, v144
	v_lshl_add_u32 v187, v187, 9, v144
	global_load_dwordx4 v[32:35], v184, s[10:11]
	global_load_dwordx4 v[36:39], v184, s[10:11] offset:256
	global_load_dwordx4 v[40:43], v185, s[10:11]
	global_load_dwordx4 v[44:47], v185, s[10:11] offset:256
	global_load_dwordx4 v[48:51], v186, s[10:11]
	global_load_dwordx4 v[52:55], v186, s[10:11] offset:256
	global_load_dwordx4 v[56:59], v187, s[10:11]
	global_load_dwordx4 v[60:63], v187, s[10:11] offset:256
	s_waitcnt vmcnt(8)
	v_mfma_scale_f32_16x16x128_f8f6f4 v[64:67], v[0:3], v[162:169], 0, v133, v133 op_sel_hi:[0,0,0] cbsz:4
	v_mfma_scale_f32_16x16x128_f8f6f4 v[64:67], v[4:7], v[170:177], v[64:67], v133, v133 op_sel_hi:[0,0,0] cbsz:4
	v_mfma_scale_f32_16x16x128_f8f6f4 v[68:71], v[8:11], v[162:169], 0, v133, v133 op_sel_hi:[0,0,0] cbsz:4
	v_mfma_scale_f32_16x16x128_f8f6f4 v[68:71], v[12:15], v[170:177], v[68:71], v133, v133 op_sel_hi:[0,0,0] cbsz:4
	v_mfma_scale_f32_16x16x128_f8f6f4 v[72:75], v[16:19], v[162:169], 0, v133, v133 op_sel_hi:[0,0,0] cbsz:4
	v_mfma_scale_f32_16x16x128_f8f6f4 v[72:75], v[20:23], v[170:177], v[72:75], v133, v133 op_sel_hi:[0,0,0] cbsz:4
	v_mfma_scale_f32_16x16x128_f8f6f4 v[76:79], v[24:27], v[162:169], 0, v133, v133 op_sel_hi:[0,0,0] cbsz:4
	v_mfma_scale_f32_16x16x128_f8f6f4 v[76:79], v[28:31], v[170:177], v[76:79], v133, v133 op_sel_hi:[0,0,0] cbsz:4
	s_nop 3
	v_mul_f32_e32 v188, v158, v80
	v_mul_f32_e32 v189, v158, v84
	v_mul_f32_e32 v190, v158, v88
	v_mul_f32_e32 v191, v158, v92
	v_fmac_f32_e32 v188, v159, v81
	v_fmac_f32_e32 v189, v159, v85
	v_fmac_f32_e32 v190, v159, v89
	v_fmac_f32_e32 v191, v159, v93
	v_fmac_f32_e32 v188, v160, v82
	v_fmac_f32_e32 v189, v160, v86
	v_fmac_f32_e32 v190, v160, v90
	v_fmac_f32_e32 v191, v160, v94
	v_fmac_f32_e32 v188, v161, v83
	v_fmac_f32_e32 v189, v161, v87
	v_fmac_f32_e32 v190, v161, v91
	v_fmac_f32_e32 v191, v161, v95
	v_add_f32_dpp v188, v188, v188 quad_perm:[1,0,3,2] row_mask:0xf bank_mask:0xf
	v_add_f32_dpp v189, v189, v189 quad_perm:[1,0,3,2] row_mask:0xf bank_mask:0xf
	v_add_f32_dpp v190, v190, v190 quad_perm:[1,0,3,2] row_mask:0xf bank_mask:0xf
	v_add_f32_dpp v191, v191, v191 quad_perm:[1,0,3,2] row_mask:0xf bank_mask:0xf
	v_add_f32_dpp v188, v188, v188 quad_perm:[2,3,0,1] row_mask:0xf bank_mask:0xf
	v_add_f32_dpp v189, v189, v189 quad_perm:[2,3,0,1] row_mask:0xf bank_mask:0xf
	v_add_f32_dpp v190, v190, v190 quad_perm:[2,3,0,1] row_mask:0xf bank_mask:0xf
	v_add_f32_dpp v191, v191, v191 quad_perm:[2,3,0,1] row_mask:0xf bank_mask:0xf
	v_add_f32_dpp v188, v188, v188 row_half_mirror row_mask:0xf bank_mask:0xf
	v_add_f32_dpp v189, v189, v189 row_half_mirror row_mask:0xf bank_mask:0xf
	v_add_f32_dpp v190, v190, v190 row_half_mirror row_mask:0xf bank_mask:0xf
	v_add_f32_dpp v191, v191, v191 row_half_mirror row_mask:0xf bank_mask:0xf
	ds_write_b32 v155, v188 offset:320
	ds_write_b32 v155, v189 offset:336
	ds_write_b32 v155, v190 offset:352
	ds_write_b32 v155, v191 offset:368
	s_waitcnt vmcnt(0)
; __device__ __forceinline__ void peer_token(const Params& P, int t, int lane, int* sidx, float* sval, const int* sid, const float* sgate, const unsigned* szero) {
;     ...
;             for (int hh = 0; hh < 2; ++hh) {
;                 f32x4 au = (f32x4){0.f, 0.f, 0.f, 0.f};
; #pragma unroll
;                 for (int st = 0; st < 4; ++st) {
;                     const uint4 a4 = abuf[T & 1][hh][st];
;                     const v8i Av = {(int)a4.x, (int)a4.y, (int)a4.z, (int)a4.w, 0, 0, 0, 0};
;                     au = __builtin_amdgcn_mfma_scale_f32_16x16x128_f8f6f4(Av, Bv[st], au, 4, 0, 0, 0x7f7f7f7f, 0, 0x7f7f7f7f);
;                 }
;                 if (owner) *(f32x4*)(sact + 16 * T + 8 * hh) = au;
;             }
;         }
;     }
;     __builtin_amdgcn_s_waitcnt(0xc07f);
;     __builtin_amdgcn_wave_barrier();
;     {
;         float* sw = (float*)sidx;
;         float wv[2];
; #pragma unroll
;         for (int hh = 0; hh < 2; ++hh) {
;             const int e = lane + 64 * hh, id = sid[e];
;             const float a = ((sw[e] + sw[128 + e]) + (sw[256 + e] + sw[384 + e])) * usc[id] * rstd;
;             wv[hh] = sgate[e] * vsc[id] * 0.5f * a * (1.f + erff(a * 0.70710678118654752f));
;         }
	v_mfma_scale_f32_16x16x128_f8f6f4 v[80:83], v[32:35], v[162:169], 0, v133, v133 op_sel_hi:[0,0,0] cbsz:4
	v_mfma_scale_f32_16x16x128_f8f6f4 v[80:83], v[36:39], v[170:177], v[80:83], v133, v133 op_sel_hi:[0,0,0] cbsz:4
	v_mfma_scale_f32_16x16x128_f8f6f4 v[84:87], v[40:43], v[162:169], 0, v133, v133 op_sel_hi:[0,0,0] cbsz:4
	v_mfma_scale_f32_16x16x128_f8f6f4 v[84:87], v[44:47], v[170:177], v[84:87], v133, v133 op_sel_hi:[0,0,0] cbsz:4
	v_mfma_scale_f32_16x16x128_f8f6f4 v[88:91], v[48:51], v[162:169], 0, v133, v133 op_sel_hi:[0,0,0] cbsz:4
	v_mfma_scale_f32_16x16x128_f8f6f4 v[88:91], v[52:55], v[170:177], v[88:91], v133, v133 op_sel_hi:[0,0,0] cbsz:4
	v_mfma_scale_f32_16x16x128_f8f6f4 v[92:95], v[56:59], v[162:169], 0, v133, v133 op_sel_hi:[0,0,0] cbsz:4
	v_mfma_scale_f32_16x16x128_f8f6f4 v[92:95], v[60:63], v[170:177], v[92:95], v133, v133 op_sel_hi:[0,0,0] cbsz:4
	s_nop 3
	v_mul_f32_e32 v188, v158, v64
	v_mul_f32_e32 v189, v158, v68
	v_mul_f32_e32 v190, v158, v72
	v_mul_f32_e32 v191, v158, v76
	v_fmac_f32_e32 v188, v159, v65
	v_fmac_f32_e32 v189, v159, v69
	v_fmac_f32_e32 v190, v159, v73
	v_fmac_f32_e32 v191, v159, v77
	v_fmac_f32_e32 v188, v160, v66
	v_fmac_f32_e32 v189, v160, v70
	v_fmac_f32_e32 v190, v160, v74
	v_fmac_f32_e32 v191, v160, v78
	v_fmac_f32_e32 v188, v161, v67
	v_fmac_f32_e32 v189, v161, v71
	v_fmac_f32_e32 v190, v161, v75
	v_fmac_f32_e32 v191, v161, v79
	v_add_f32_dpp v188, v188, v188 quad_perm:[1,0,3,2] row_mask:0xf bank_mask:0xf
	v_add_f32_dpp v189, v189, v189 quad_perm:[1,0,3,2] row_mask:0xf bank_mask:0xf
	v_add_f32_dpp v190, v190, v190 quad_perm:[1,0,3,2] row_mask:0xf bank_mask:0xf
	v_add_f32_dpp v191, v191, v191 quad_perm:[1,0,3,2] row_mask:0xf bank_mask:0xf
	v_add_f32_dpp v188, v188, v188 quad_perm:[2,3,0,1] row_mask:0xf bank_mask:0xf
	v_add_f32_dpp v189, v189, v189 quad_perm:[2,3,0,1] row_mask:0xf bank_mask:0xf
	v_add_f32_dpp v190, v190, v190 quad_perm:[2,3,0,1] row_mask:0xf bank_mask:0xf
	v_add_f32_dpp v191, v191, v191 quad_perm:[2,3,0,1] row_mask:0xf bank_mask:0xf
	v_add_f32_dpp v188, v188, v188 row_half_mirror row_mask:0xf bank_mask:0xf
	v_add_f32_dpp v189, v189, v189 row_half_mirror row_mask:0xf bank_mask:0xf
	v_add_f32_dpp v190, v190, v190 row_half_mirror row_mask:0xf bank_mask:0xf
	v_add_f32_dpp v191, v191, v191 row_half_mirror row_mask:0xf bank_mask:0xf
	ds_write_b32 v155, v188 offset:384
	ds_write_b32 v155, v189 offset:400
	ds_write_b32 v155, v190 offset:416
	ds_write_b32 v155, v191 offset:432
	s_nop 11
	v_mul_f32_e32 v188, v158, v80
	v_mul_f32_e32 v189, v158, v84
	v_mul_f32_e32 v190, v158, v88
	v_mul_f32_e32 v191, v158, v92
	v_fmac_f32_e32 v188, v159, v81
	v_fmac_f32_e32 v189, v159, v85
	v_fmac_f32_e32 v190, v159, v89
	v_fmac_f32_e32 v191, v159, v93
	v_fmac_f32_e32 v188, v160, v82
	v_fmac_f32_e32 v189, v160, v86
	v_fmac_f32_e32 v190, v160, v90
	v_fmac_f32_e32 v191, v160, v94
	v_fmac_f32_e32 v188, v161, v83
	v_fmac_f32_e32 v189, v161, v87
	v_fmac_f32_e32 v190, v161, v91
	v_fmac_f32_e32 v191, v161, v95
	v_add_f32_dpp v188, v188, v188 quad_perm:[1,0,3,2] row_mask:0xf bank_mask:0xf
	v_add_f32_dpp v189, v189, v189 quad_perm:[1,0,3,2] row_mask:0xf bank_mask:0xf
	v_add_f32_dpp v190, v190, v190 quad_perm:[1,0,3,2] row_mask:0xf bank_mask:0xf
	v_add_f32_dpp v191, v191, v191 quad_perm:[1,0,3,2] row_mask:0xf bank_mask:0xf
	v_add_f32_dpp v188, v188, v188 quad_perm:[2,3,0,1] row_mask:0xf bank_mask:0xf
	v_add_f32_dpp v189, v189, v189 quad_perm:[2,3,0,1] row_mask:0xf bank_mask:0xf
	v_add_f32_dpp v190, v190, v190 quad_perm:[2,3,0,1] row_mask:0xf bank_mask:0xf
	v_add_f32_dpp v191, v191, v191 quad_perm:[2,3,0,1] row_mask:0xf bank_mask:0xf
	v_add_f32_dpp v188, v188, v188 row_half_mirror row_mask:0xf bank_mask:0xf
	v_add_f32_dpp v189, v189, v189 row_half_mirror row_mask:0xf bank_mask:0xf
	v_add_f32_dpp v190, v190, v190 row_half_mirror row_mask:0xf bank_mask:0xf
	v_add_f32_dpp v191, v191, v191 row_half_mirror row_mask:0xf bank_mask:0xf
	ds_write_b32 v155, v188 offset:448
	ds_write_b32 v155, v189 offset:464
	ds_write_b32 v155, v190 offset:480
	ds_write_b32 v155, v191 offset:496
	v_lshl_add_u32 v2, v131, 2, v139
	s_waitcnt lgkmcnt(0)
	ds_read2st64_b32 v[0:1], v2 offset1:2
	s_waitcnt lgkmcnt(0)
	v_ashrrev_i32_e32 v5, 31, v0
	v_mov_b32_e32 v4, v0
	v_lshlrev_b64 v[4:5], 2, v[4:5]
	v_lshl_add_u64 v[6:7], s[8:9], 0, v[4:5]
	global_load_dword v3, v[6:7], off
	v_lshl_add_u64 v[4:5], s[6:7], 0, v[4:5]
	global_load_dword v0, v[4:5], off
	ds_read_b32 v4, v135 offset:8192
	s_waitcnt lgkmcnt(0)
	s_waitcnt vmcnt(1)
	v_mul_f32_e32 v3, v3, v4
	v_mul_f32_e32 v4, v140, v3
	v_mul_f32_e32 v5, 0x3f3504f3, v4
	v_cmp_nlt_f32_e64 s[18:19], |v5|, 1.0
	s_and_saveexec_b64 s[86:87], s[18:19]
	s_xor_b64 s[18:19], exec, s[86:87]
	s_cbranch_execz .LBB0_1417
	v_fma_f32 v3, |v5|, s74, v136
	v_fma_f32 v3, |v5|, v3, s75
	v_fma_f32 v3, |v5|, v3, s76
	v_fma_f32 v3, |v5|, v3, s77
	v_fma_f32 v3, |v5|, v3, s78
	v_fma_f32 v3, |v5|, v3, s79
	v_fma_f32 v3, |v5|, v3, |v5|
	v_mul_f32_e32 v6, 0xbfb8aa3b, v3
	v_fma_f32 v7, v3, s80, -v6
	v_rndne_f32_e32 v8, v6
	v_fmac_f32_e32 v7, 0xb2a5705f, v3
	v_sub_f32_e32 v6, v6, v8
	v_add_f32_e32 v6, v6, v7
	v_cvt_i32_f32_e32 v7, v8
	v_exp_f32_e32 v6, v6
	v_cmp_nlt_f32_e32 vcc, s81, v3
	v_ldexp_f32 v6, v6, v7
	s_nop 0
	v_cndmask_b32_e32 v6, 0, v6, vcc
	v_cmp_ngt_f32_e32 vcc, s82, v3
	s_nop 1
	v_cndmask_b32_e32 v3, v137, v6, vcc
	v_sub_f32_e32 v6, 1.0, v3
.LBB0_1417:
	s_andn2_saveexec_b64 s[18:19], s[18:19]
	v_mul_f32_e32 v3, v5, v5
	v_fmamk_f32 v6, v3, 0xba1345e1, v134
	v_fmaak_f32 v6, v3, v6, 0xbcdac9b8
	v_fmaak_f32 v6, v3, v6, 0x3de703be
	v_fmaak_f32 v6, v3, v6, 0xbec09330
	v_fmaak_f32 v3, v3, v6, 0x3e0375d0
	v_fma_f32 v6, |v5|, v3, |v5|
	s_or_b64 exec, exec, s[18:19]
	ds_read2st64_b32 v[2:3], v2 offset0:1 offset1:3
	s_waitcnt lgkmcnt(0)
	v_ashrrev_i32_e32 v9, 31, v2
	v_mov_b32_e32 v8, v2
	v_lshlrev_b64 v[8:9], 2, v[8:9]
	v_lshl_add_u64 v[10:11], s[8:9], 0, v[8:9]
	global_load_dword v7, v[10:11], off
	v_lshl_add_u64 v[8:9], s[6:7], 0, v[8:9]
	global_load_dword v2, v[8:9], off
	ds_read_b32 v8, v135 offset:8448
	s_waitcnt lgkmcnt(0)
	s_waitcnt vmcnt(1)
	v_mul_f32_e32 v7, v7, v8
	v_mul_f32_e32 v7, v140, v7
	v_mul_f32_e32 v8, 0x3f3504f3, v7
	v_cmp_nlt_f32_e64 s[18:19], |v8|, 1.0
	s_and_saveexec_b64 s[86:87], s[18:19]
	s_xor_b64 s[18:19], exec, s[86:87]
	s_cbranch_execz .LBB0_1421
	v_fma_f32 v9, |v8|, s74, v136
	v_fma_f32 v9, |v8|, v9, s75
	v_fma_f32 v9, |v8|, v9, s76
	v_fma_f32 v9, |v8|, v9, s77
	v_fma_f32 v9, |v8|, v9, s78
	v_fma_f32 v9, |v8|, v9, s79
	v_fma_f32 v9, |v8|, v9, |v8|
	v_mul_f32_e32 v10, 0xbfb8aa3b, v9
	v_fma_f32 v11, v9, s80, -v10
	v_rndne_f32_e32 v12, v10
	v_fmac_f32_e32 v11, 0xb2a5705f, v9
	v_sub_f32_e32 v10, v10, v12
	v_add_f32_e32 v10, v10, v11
	v_cvt_i32_f32_e32 v11, v12
	v_exp_f32_e32 v10, v10
	v_cmp_nlt_f32_e32 vcc, s81, v9
	v_ldexp_f32 v10, v10, v11
	s_nop 0
	v_cndmask_b32_e32 v10, 0, v10, vcc
	v_cmp_ngt_f32_e32 vcc, s82, v9
	s_nop 1
	v_cndmask_b32_e32 v9, v137, v10, vcc
	v_sub_f32_e32 v9, 1.0, v9
